# nt on the streaming residual-x loads of the de-serialised output-projection epilogue
# speedup vs baseline: 1.0084x; 1.0084x over previous
;     __device__ __forceinline__ void operator()(const f32x4 (&acc)[2][2][4][2], const pg8::Unit& u, int wr, int wc, int fr, int fq) const {
;     ...
; #pragma unroll
;         for (int ai = 0; ai < 2; ++ai)
; #pragma unroll
;             for (int m = 0; m < 4; ++m) { const size_t row = (size_t)(row0 + ai * 128 + m * 16);
; #pragma unroll
;                 for (int bj = 0; bj < 2; ++bj) { const size_t off = row * 2048 + col0 + bj * 128;
;                     const f32x4 x0 = *(const f32x4*)(X + off), x1 = *(const f32x4*)(X + off + 4);
;                     *(f32x4*)(Y + off) = x0 * ALPHA + acc[ai][bj][m][0]; *(f32x4*)(Y + off + 4) = x1 * ALPHA + acc[ai][bj][m][1]; } }
.LBB0_1064:
	v_lshl_add_u32 v160, s40, 8, v146
	v_lshl_or_b32 v162, s61, 8, v148
	v_ashrrev_i32_e32 v161, 31, v160
	v_ashrrev_i32_e32 v163, 31, v162
	v_lshlrev_b64 v[144:145], 11, v[160:161]
	v_lshl_add_u64 v[144:145], v[144:145], 0, v[162:163]
	v_lshlrev_b64 v[144:145], 2, v[144:145]
	v_lshl_add_u64 v[244:245], s[36:37], 0, v[144:145]
	v_lshl_add_u64 v[246:247], s[54:55], 0, v[144:145]
	v_mov_b32_e32 v250, 0x20000
	v_mov_b32_e32 v251, 0
	v_mov_b32_e32 v248, 0xa0000
	v_mov_b32_e32 v249, 0
	s_andn2_b64 vcc, exec, s[0:1]
	s_mov_b64 s[0:1], -1
	global_load_dwordx4 v[168:171], v[244:245], off nt
	global_load_dwordx4 v[172:175], v[244:245], off offset:16 nt
	global_load_dwordx4 v[176:179], v[244:245], off offset:512 nt
	global_load_dwordx4 v[180:183], v[244:245], off offset:528 nt
	v_lshl_add_u64 v[244:245], v[244:245], 0, v[250:251]
	global_load_dwordx4 v[184:187], v[244:245], off nt
	global_load_dwordx4 v[190:193], v[244:245], off offset:16 nt
	global_load_dwordx4 v[194:197], v[244:245], off offset:512 nt
	global_load_dwordx4 v[198:201], v[244:245], off offset:528 nt
	v_lshl_add_u64 v[244:245], v[244:245], 0, v[250:251]
	global_load_dwordx4 v[202:205], v[244:245], off nt
	global_load_dwordx4 v[208:211], v[244:245], off offset:16 nt
	global_load_dwordx4 v[212:215], v[244:245], off offset:512 nt
	global_load_dwordx4 v[216:219], v[244:245], off offset:528 nt
	v_lshl_add_u64 v[244:245], v[244:245], 0, v[250:251]
	global_load_dwordx4 v[228:231], v[244:245], off nt
	global_load_dwordx4 v[232:235], v[244:245], off offset:16 nt
	global_load_dwordx4 v[236:239], v[244:245], off offset:512 nt
	global_load_dwordx4 v[240:243], v[244:245], off offset:528 nt
	v_lshl_add_u64 v[244:245], v[244:245], 0, v[248:249]
	s_waitcnt vmcnt(14)
	v_pk_fma_f32 v[124:125], v[168:169], s[12:13], v[124:125] op_sel_hi:[1,0,1]
	v_pk_fma_f32 v[126:127], v[170:171], s[12:13], v[126:127] op_sel_hi:[1,0,1]
	v_pk_fma_f32 v[120:121], v[172:173], s[12:13], v[120:121] op_sel_hi:[1,0,1]
	v_pk_fma_f32 v[122:123], v[174:175], s[12:13], v[122:123] op_sel_hi:[1,0,1]
	global_store_dwordx4 v[246:247], v[124:127], off
	global_store_dwordx4 v[246:247], v[120:123], off offset:16
	global_load_dwordx4 v[168:171], v[244:245], off nt
	global_load_dwordx4 v[172:175], v[244:245], off offset:16 nt
	s_waitcnt vmcnt(16)
	v_pk_fma_f32 v[112:113], v[176:177], s[12:13], v[112:113] op_sel_hi:[1,0,1]
	v_pk_fma_f32 v[114:115], v[178:179], s[12:13], v[114:115] op_sel_hi:[1,0,1]
	v_pk_fma_f32 v[108:109], v[180:181], s[12:13], v[108:109] op_sel_hi:[1,0,1]
	v_pk_fma_f32 v[110:111], v[182:183], s[12:13], v[110:111] op_sel_hi:[1,0,1]
	global_store_dwordx4 v[246:247], v[112:115], off offset:512
	global_store_dwordx4 v[246:247], v[108:111], off offset:528
	v_lshl_add_u64 v[246:247], v[246:247], 0, v[250:251]
	global_load_dwordx4 v[176:179], v[244:245], off offset:512 nt
	global_load_dwordx4 v[180:183], v[244:245], off offset:528 nt
	v_lshl_add_u64 v[244:245], v[244:245], 0, v[250:251]
	s_waitcnt vmcnt(18)
	v_pk_fma_f32 v[116:117], v[184:185], s[12:13], v[116:117] op_sel_hi:[1,0,1]
	v_pk_fma_f32 v[118:119], v[186:187], s[12:13], v[118:119] op_sel_hi:[1,0,1]
	v_pk_fma_f32 v[104:105], v[190:191], s[12:13], v[104:105] op_sel_hi:[1,0,1]
	v_pk_fma_f32 v[106:107], v[192:193], s[12:13], v[106:107] op_sel_hi:[1,0,1]
	global_store_dwordx4 v[246:247], v[116:119], off
	global_store_dwordx4 v[246:247], v[104:107], off offset:16
	global_load_dwordx4 v[184:187], v[244:245], off nt
	global_load_dwordx4 v[190:193], v[244:245], off offset:16 nt
	s_waitcnt vmcnt(20)
	v_pk_fma_f32 v[96:97], v[194:195], s[12:13], v[96:97] op_sel_hi:[1,0,1]
	v_pk_fma_f32 v[98:99], v[196:197], s[12:13], v[98:99] op_sel_hi:[1,0,1]
	v_pk_fma_f32 v[92:93], v[198:199], s[12:13], v[92:93] op_sel_hi:[1,0,1]
	v_pk_fma_f32 v[94:95], v[200:201], s[12:13], v[94:95] op_sel_hi:[1,0,1]
	global_store_dwordx4 v[246:247], v[96:99], off offset:512
	global_store_dwordx4 v[246:247], v[92:95], off offset:528
	v_lshl_add_u64 v[246:247], v[246:247], 0, v[250:251]
	global_load_dwordx4 v[194:197], v[244:245], off offset:512 nt
	global_load_dwordx4 v[198:201], v[244:245], off offset:528 nt
	v_lshl_add_u64 v[244:245], v[244:245], 0, v[250:251]
	s_waitcnt vmcnt(22)
	v_pk_fma_f32 v[100:101], v[202:203], s[12:13], v[100:101] op_sel_hi:[1,0,1]
	v_pk_fma_f32 v[102:103], v[204:205], s[12:13], v[102:103] op_sel_hi:[1,0,1]
	v_pk_fma_f32 v[88:89], v[208:209], s[12:13], v[88:89] op_sel_hi:[1,0,1]
	v_pk_fma_f32 v[90:91], v[210:211], s[12:13], v[90:91] op_sel_hi:[1,0,1]
	global_store_dwordx4 v[246:247], v[100:103], off
	global_store_dwordx4 v[246:247], v[88:91], off offset:16
	global_load_dwordx4 v[202:205], v[244:245], off nt
	global_load_dwordx4 v[208:211], v[244:245], off offset:16 nt
	s_waitcnt vmcnt(24)
	v_pk_fma_f32 v[80:81], v[212:213], s[12:13], v[80:81] op_sel_hi:[1,0,1]
	v_pk_fma_f32 v[82:83], v[214:215], s[12:13], v[82:83] op_sel_hi:[1,0,1]
	v_pk_fma_f32 v[76:77], v[216:217], s[12:13], v[76:77] op_sel_hi:[1,0,1]
	v_pk_fma_f32 v[78:79], v[218:219], s[12:13], v[78:79] op_sel_hi:[1,0,1]
	global_store_dwordx4 v[246:247], v[80:83], off offset:512
	global_store_dwordx4 v[246:247], v[76:79], off offset:528
	v_lshl_add_u64 v[246:247], v[246:247], 0, v[250:251]
	global_load_dwordx4 v[212:215], v[244:245], off offset:512 nt
	global_load_dwordx4 v[216:219], v[244:245], off offset:528 nt
	v_lshl_add_u64 v[244:245], v[244:245], 0, v[250:251]
	s_waitcnt vmcnt(26)
;     __device__ __forceinline__ void operator()(const f32x4 (&acc)[2][2][4][2], const pg8::Unit& u, int wr, int wc, int fr, int fq) const {
;     ...
; #pragma unroll
;         for (int ai = 0; ai < 2; ++ai)
; #pragma unroll
;             for (int m = 0; m < 4; ++m) { const size_t row = (size_t)(row0 + ai * 128 + m * 16);
; #pragma unroll
;                 for (int bj = 0; bj < 2; ++bj) { const size_t off = row * 2048 + col0 + bj * 128;
;                     const f32x4 x0 = *(const f32x4*)(X + off), x1 = *(const f32x4*)(X + off + 4);
;                     *(f32x4*)(Y + off) = x0 * ALPHA + acc[ai][bj][m][0]; *(f32x4*)(Y + off + 4) = x1 * ALPHA + acc[ai][bj][m][1]; } }
	v_pk_fma_f32 v[84:85], v[228:229], s[12:13], v[84:85] op_sel_hi:[1,0,1]
	v_pk_fma_f32 v[86:87], v[230:231], s[12:13], v[86:87] op_sel_hi:[1,0,1]
	v_pk_fma_f32 v[72:73], v[232:233], s[12:13], v[72:73] op_sel_hi:[1,0,1]
	v_pk_fma_f32 v[74:75], v[234:235], s[12:13], v[74:75] op_sel_hi:[1,0,1]
	global_store_dwordx4 v[246:247], v[84:87], off
	global_store_dwordx4 v[246:247], v[72:75], off offset:16
	global_load_dwordx4 v[228:231], v[244:245], off nt
	global_load_dwordx4 v[232:235], v[244:245], off offset:16 nt
	s_waitcnt vmcnt(28)
	v_pk_fma_f32 v[68:69], v[236:237], s[12:13], v[68:69] op_sel_hi:[1,0,1]
	v_pk_fma_f32 v[70:71], v[238:239], s[12:13], v[70:71] op_sel_hi:[1,0,1]
	v_pk_fma_f32 v[64:65], v[240:241], s[12:13], v[64:65] op_sel_hi:[1,0,1]
	v_pk_fma_f32 v[66:67], v[242:243], s[12:13], v[66:67] op_sel_hi:[1,0,1]
	global_store_dwordx4 v[246:247], v[68:71], off offset:512
	global_store_dwordx4 v[246:247], v[64:67], off offset:528
	v_lshl_add_u64 v[246:247], v[246:247], 0, v[248:249]
	global_load_dwordx4 v[236:239], v[244:245], off offset:512 nt
	global_load_dwordx4 v[240:243], v[244:245], off offset:528 nt
	v_lshl_add_u64 v[244:245], v[244:245], 0, v[250:251]
	s_waitcnt vmcnt(28)
	v_pk_fma_f32 v[60:61], v[168:169], s[12:13], v[60:61] op_sel_hi:[1,0,1]
	v_pk_fma_f32 v[62:63], v[170:171], s[12:13], v[62:63] op_sel_hi:[1,0,1]
	v_pk_fma_f32 v[56:57], v[172:173], s[12:13], v[56:57] op_sel_hi:[1,0,1]
	v_pk_fma_f32 v[58:59], v[174:175], s[12:13], v[58:59] op_sel_hi:[1,0,1]
	global_store_dwordx4 v[246:247], v[60:63], off
	global_store_dwordx4 v[246:247], v[56:59], off offset:16
	s_waitcnt vmcnt(26)
	v_pk_fma_f32 v[48:49], v[176:177], s[12:13], v[48:49] op_sel_hi:[1,0,1]
	v_pk_fma_f32 v[50:51], v[178:179], s[12:13], v[50:51] op_sel_hi:[1,0,1]
	v_pk_fma_f32 v[44:45], v[180:181], s[12:13], v[44:45] op_sel_hi:[1,0,1]
	v_pk_fma_f32 v[46:47], v[182:183], s[12:13], v[46:47] op_sel_hi:[1,0,1]
	global_store_dwordx4 v[246:247], v[48:51], off offset:512
	global_store_dwordx4 v[246:247], v[44:47], off offset:528
	v_lshl_add_u64 v[246:247], v[246:247], 0, v[250:251]
	s_waitcnt vmcnt(24)
	v_pk_fma_f32 v[52:53], v[184:185], s[12:13], v[52:53] op_sel_hi:[1,0,1]
	v_pk_fma_f32 v[54:55], v[186:187], s[12:13], v[54:55] op_sel_hi:[1,0,1]
	v_pk_fma_f32 v[40:41], v[190:191], s[12:13], v[40:41] op_sel_hi:[1,0,1]
	v_pk_fma_f32 v[42:43], v[192:193], s[12:13], v[42:43] op_sel_hi:[1,0,1]
	global_store_dwordx4 v[246:247], v[52:55], off
	global_store_dwordx4 v[246:247], v[40:43], off offset:16
	s_waitcnt vmcnt(22)
	v_pk_fma_f32 v[32:33], v[194:195], s[12:13], v[32:33] op_sel_hi:[1,0,1]
	v_pk_fma_f32 v[34:35], v[196:197], s[12:13], v[34:35] op_sel_hi:[1,0,1]
	v_pk_fma_f32 v[28:29], v[198:199], s[12:13], v[28:29] op_sel_hi:[1,0,1]
	v_pk_fma_f32 v[30:31], v[200:201], s[12:13], v[30:31] op_sel_hi:[1,0,1]
	global_store_dwordx4 v[246:247], v[32:35], off offset:512
	global_store_dwordx4 v[246:247], v[28:31], off offset:528
	v_lshl_add_u64 v[246:247], v[246:247], 0, v[250:251]
	s_waitcnt vmcnt(20)
	v_pk_fma_f32 v[36:37], v[202:203], s[12:13], v[36:37] op_sel_hi:[1,0,1]
	v_pk_fma_f32 v[38:39], v[204:205], s[12:13], v[38:39] op_sel_hi:[1,0,1]
	v_pk_fma_f32 v[24:25], v[208:209], s[12:13], v[24:25] op_sel_hi:[1,0,1]
	v_pk_fma_f32 v[26:27], v[210:211], s[12:13], v[26:27] op_sel_hi:[1,0,1]
	global_store_dwordx4 v[246:247], v[36:39], off
	global_store_dwordx4 v[246:247], v[24:27], off offset:16
	s_waitcnt vmcnt(18)
	v_pk_fma_f32 v[16:17], v[212:213], s[12:13], v[16:17] op_sel_hi:[1,0,1]
	v_pk_fma_f32 v[18:19], v[214:215], s[12:13], v[18:19] op_sel_hi:[1,0,1]
	v_pk_fma_f32 v[12:13], v[216:217], s[12:13], v[12:13] op_sel_hi:[1,0,1]
	v_pk_fma_f32 v[14:15], v[218:219], s[12:13], v[14:15] op_sel_hi:[1,0,1]
	global_store_dwordx4 v[246:247], v[16:19], off offset:512
	global_store_dwordx4 v[246:247], v[12:15], off offset:528
	v_lshl_add_u64 v[246:247], v[246:247], 0, v[250:251]
	s_waitcnt vmcnt(16)
	v_pk_fma_f32 v[20:21], v[228:229], s[12:13], v[20:21] op_sel_hi:[1,0,1]
	v_pk_fma_f32 v[22:23], v[230:231], s[12:13], v[22:23] op_sel_hi:[1,0,1]
	v_pk_fma_f32 v[8:9], v[232:233], s[12:13], v[8:9] op_sel_hi:[1,0,1]
	v_pk_fma_f32 v[10:11], v[234:235], s[12:13], v[10:11] op_sel_hi:[1,0,1]
	global_store_dwordx4 v[246:247], v[20:23], off
	global_store_dwordx4 v[246:247], v[8:11], off offset:16
	s_waitcnt vmcnt(14)
	v_pk_fma_f32 v[4:5], v[236:237], s[12:13], v[4:5] op_sel_hi:[1,0,1]
	v_pk_fma_f32 v[6:7], v[238:239], s[12:13], v[6:7] op_sel_hi:[1,0,1]
	v_pk_fma_f32 v[0:1], v[240:241], s[12:13], v[0:1] op_sel_hi:[1,0,1]
	v_pk_fma_f32 v[2:3], v[242:243], s[12:13], v[2:3] op_sel_hi:[1,0,1]
	global_store_dwordx4 v[246:247], v[4:7], off offset:512
	global_store_dwordx4 v[246:247], v[0:3], off offset:528
	v_lshl_add_u64 v[246:247], v[246:247], 0, v[250:251]
	s_nop 0
	s_nop 0
	s_nop 0
	s_nop 0
	s_cbranch_vccnz .LBB0_1053
	s_andn2_b64 vcc, exec, s[6:7]
	s_cbranch_vccnz .LBB0_1052
	s_barrier
	s_branch .LBB0_1052
